# stack + GEMM<1> epilogue: redundant per-column factor reloads and their waits removed (8 per tile)
# baseline (speedup 1.0000x reference)
.Lg910_loop:
	s_waitcnt lgkmcnt(4)
	v_mfma_f32_32x32x16_bf16 v[114:129], v[150:153], v[166:169], v[114:129]
	ds_read_b128 v[174:177], v206 offset:0
	s_waitcnt lgkmcnt(4)
	v_mfma_f32_32x32x16_bf16 v[98:113], v[150:153], v[170:173], v[98:113]
	ds_read_b128 v[192:195], v210 offset:0
	s_add_u32 m0, s14, 0x1a020
	s_add_u32 s12, s12, 0x20000
	s_addc_u32 s13, s13, 0
	global_load_lds_dwordx4 v149, s[12:13]
	s_waitcnt lgkmcnt(4)
	v_mfma_f32_32x32x16_bf16 v[82:97], v[154:157], v[166:169], v[82:97]
	ds_read_b128 v[200:203], v210 offset:4096
	v_mfma_f32_32x32x16_bf16 v[66:81], v[154:157], v[170:173], v[66:81]
	ds_read_b128 v[180:183], v206 offset:4096
	s_add_u32 m0, s14, 0x1c020
	s_add_u32 s12, s12, 0x20000
	s_addc_u32 s13, s13, 0
	global_load_lds_dwordx4 v149, s[12:13]
	s_waitcnt lgkmcnt(5)
	v_mfma_f32_32x32x16_bf16 v[50:65], v[158:161], v[166:169], v[50:65]
	ds_read_b128 v[184:187], v206 offset:8192
	v_mfma_f32_32x32x16_bf16 v[34:49], v[158:161], v[170:173], v[34:49]
	ds_read_b128 v[188:191], v206 offset:12288
	s_add_u32 m0, s14, 0x1e020
	s_add_u32 s12, s12, 0x20000
	s_addc_u32 s13, s13, 0
	global_load_lds_dwordx4 v149, s[12:13]
	s_add_u32 s4, s4, 0x80
	s_addc_u32 s5, s5, 0
	s_waitcnt lgkmcnt(6)
	v_mfma_f32_32x32x16_bf16 v[18:33], v[162:165], v[166:169], v[18:33]
	v_mfma_f32_32x32x16_bf16 v[2:17], v[162:165], v[170:173], v[2:17]
	s_waitcnt lgkmcnt(4)
	v_mfma_f32_32x32x16_bf16 v[114:129], v[174:177], v[192:195], v[114:129]
	ds_read_b128 v[150:153], v207 offset:0
	s_waitcnt lgkmcnt(4)
	v_mfma_f32_32x32x16_bf16 v[98:113], v[174:177], v[200:203], v[98:113]
	ds_read_b128 v[166:169], v211 offset:0
	s_waitcnt lgkmcnt(4)
	v_mfma_f32_32x32x16_bf16 v[82:97], v[180:183], v[192:195], v[82:97]
	ds_read_b128 v[170:173], v211 offset:4096
	v_mfma_f32_32x32x16_bf16 v[66:81], v[180:183], v[200:203], v[66:81]
	ds_read_b128 v[154:157], v207 offset:4096
	s_waitcnt lgkmcnt(5)
	v_mfma_f32_32x32x16_bf16 v[50:65], v[184:187], v[192:195], v[50:65]
	ds_read_b128 v[158:161], v207 offset:8192
	v_mfma_f32_32x32x16_bf16 v[34:49], v[184:187], v[200:203], v[34:49]
	ds_read_b128 v[162:165], v207 offset:12288
	s_waitcnt lgkmcnt(6)
	v_mfma_f32_32x32x16_bf16 v[18:33], v[188:191], v[192:195], v[18:33]
	v_mfma_f32_32x32x16_bf16 v[2:17], v[188:191], v[200:203], v[2:17]
	s_waitcnt lgkmcnt(4)
	v_mfma_f32_32x32x16_bf16 v[114:129], v[150:153], v[166:169], v[114:129]
	ds_read_b128 v[174:177], v208 offset:0
	ds_read_b128 v[192:195], v212 offset:0
	s_waitcnt lgkmcnt(5)
	v_mfma_f32_32x32x16_bf16 v[98:113], v[150:153], v[170:173], v[98:113]
	ds_read_b128 v[200:203], v212 offset:4096
	ds_read_b128 v[180:183], v208 offset:4096
	s_waitcnt lgkmcnt(6)
	v_mfma_f32_32x32x16_bf16 v[82:97], v[154:157], v[166:169], v[82:97]
	ds_read_b128 v[184:187], v208 offset:8192
	ds_read_b128 v[188:191], v208 offset:12288
	v_mfma_f32_32x32x16_bf16 v[66:81], v[154:157], v[170:173], v[66:81]
	s_waitcnt lgkmcnt(7)
	v_mfma_f32_32x32x16_bf16 v[50:65], v[158:161], v[166:169], v[50:65]
	v_mfma_f32_32x32x16_bf16 v[34:49], v[158:161], v[170:173], v[34:49]
	s_waitcnt lgkmcnt(6)
	v_mfma_f32_32x32x16_bf16 v[18:33], v[162:165], v[166:169], v[18:33]
	v_mfma_f32_32x32x16_bf16 v[2:17], v[162:165], v[170:173], v[2:17]
	s_waitcnt vmcnt(0) lgkmcnt(0)
	s_barrier
	v_mfma_f32_32x32x16_bf16 v[114:129], v[174:177], v[192:195], v[114:129]
	ds_read_b128 v[150:153], v205 offset:32768
	s_add_u32 m0, s14, 0x20
	s_add_u32 s12, s1, s4
	s_addc_u32 s13, s3, s5
	global_load_lds_dwordx4 v149, s[12:13]
	v_mfma_f32_32x32x16_bf16 v[98:113], v[174:177], v[200:203], v[98:113]
	ds_read_b128 v[166:169], v209 offset:32768
	s_add_u32 m0, s14, 0x2020
	s_add_u32 s12, s12, 0x20000
	s_addc_u32 s13, s13, 0
	global_load_lds_dwordx4 v149, s[12:13]
	v_mfma_f32_32x32x16_bf16 v[82:97], v[180:183], v[192:195], v[82:97]
	ds_read_b128 v[170:173], v209 offset:36864
	s_add_u32 m0, s14, 0x4020
	s_add_u32 s12, s12, 0x20000
	s_addc_u32 s13, s13, 0
	global_load_lds_dwordx4 v149, s[12:13]
	v_mfma_f32_32x32x16_bf16 v[66:81], v[180:183], v[200:203], v[66:81]
	ds_read_b128 v[154:157], v205 offset:36864
	s_add_u32 m0, s14, 0x6020
	s_add_u32 s12, s12, 0x20000
	s_addc_u32 s13, s13, 0
	global_load_lds_dwordx4 v149, s[12:13]
	v_mfma_f32_32x32x16_bf16 v[50:65], v[184:187], v[192:195], v[50:65]
	ds_read_b128 v[158:161], v205 offset:40960
	s_add_u32 m0, s14, 0x10020
	s_add_u32 s12, s10, s4
	s_addc_u32 s13, s11, s5
	global_load_lds_dwordx4 v149, s[12:13]
	v_mfma_f32_32x32x16_bf16 v[34:49], v[184:187], v[200:203], v[34:49]
	ds_read_b128 v[162:165], v205 offset:45056
	v_mfma_f32_32x32x16_bf16 v[18:33], v[188:191], v[192:195], v[18:33]
	v_mfma_f32_32x32x16_bf16 v[2:17], v[188:191], v[200:203], v[2:17]
	s_waitcnt lgkmcnt(4)
	v_mfma_f32_32x32x16_bf16 v[114:129], v[150:153], v[166:169], v[114:129]
	ds_read_b128 v[174:177], v206 offset:32768
	s_waitcnt lgkmcnt(4)
	v_mfma_f32_32x32x16_bf16 v[98:113], v[150:153], v[170:173], v[98:113]
	ds_read_b128 v[192:195], v210 offset:32768
	s_add_u32 m0, s14, 0x12020
	s_add_u32 s12, s12, 0x20000
	s_addc_u32 s13, s13, 0
	global_load_lds_dwordx4 v149, s[12:13]
	s_waitcnt lgkmcnt(4)
	v_mfma_f32_32x32x16_bf16 v[82:97], v[154:157], v[166:169], v[82:97]
	ds_read_b128 v[200:203], v210 offset:36864
	v_mfma_f32_32x32x16_bf16 v[66:81], v[154:157], v[170:173], v[66:81]
	ds_read_b128 v[180:183], v206 offset:36864
	s_add_u32 m0, s14, 0x14020
	s_add_u32 s12, s12, 0x20000
	s_addc_u32 s13, s13, 0
	global_load_lds_dwordx4 v149, s[12:13]
	s_waitcnt lgkmcnt(5)
	v_mfma_f32_32x32x16_bf16 v[50:65], v[158:161], v[166:169], v[50:65]
	ds_read_b128 v[184:187], v206 offset:40960
	v_mfma_f32_32x32x16_bf16 v[34:49], v[158:161], v[170:173], v[34:49]
	ds_read_b128 v[188:191], v206 offset:45056
	s_add_u32 m0, s14, 0x16020
	s_add_u32 s12, s12, 0x20000
	s_addc_u32 s13, s13, 0
	global_load_lds_dwordx4 v149, s[12:13]
	s_add_u32 s4, s4, 0x80
	s_addc_u32 s5, s5, 0
	s_waitcnt lgkmcnt(6)
	v_mfma_f32_32x32x16_bf16 v[18:33], v[162:165], v[166:169], v[18:33]
	v_mfma_f32_32x32x16_bf16 v[2:17], v[162:165], v[170:173], v[2:17]
	s_waitcnt lgkmcnt(4)
	v_mfma_f32_32x32x16_bf16 v[114:129], v[174:177], v[192:195], v[114:129]
	ds_read_b128 v[150:153], v207 offset:32768
	s_waitcnt lgkmcnt(4)
	v_mfma_f32_32x32x16_bf16 v[98:113], v[174:177], v[200:203], v[98:113]
	ds_read_b128 v[166:169], v211 offset:32768
	s_waitcnt lgkmcnt(4)
	v_mfma_f32_32x32x16_bf16 v[82:97], v[180:183], v[192:195], v[82:97]
	ds_read_b128 v[170:173], v211 offset:36864
	v_mfma_f32_32x32x16_bf16 v[66:81], v[180:183], v[200:203], v[66:81]
	ds_read_b128 v[154:157], v207 offset:36864
	s_waitcnt lgkmcnt(5)
	v_mfma_f32_32x32x16_bf16 v[50:65], v[184:187], v[192:195], v[50:65]
	ds_read_b128 v[158:161], v207 offset:40960
	v_mfma_f32_32x32x16_bf16 v[34:49], v[184:187], v[200:203], v[34:49]
	ds_read_b128 v[162:165], v207 offset:45056
	s_waitcnt lgkmcnt(6)
	v_mfma_f32_32x32x16_bf16 v[18:33], v[188:191], v[192:195], v[18:33]
	v_mfma_f32_32x32x16_bf16 v[2:17], v[188:191], v[200:203], v[2:17]
	s_waitcnt lgkmcnt(4)
	v_mfma_f32_32x32x16_bf16 v[114:129], v[150:153], v[166:169], v[114:129]
	ds_read_b128 v[174:177], v208 offset:32768
	ds_read_b128 v[192:195], v212 offset:32768
	s_waitcnt lgkmcnt(5)
	v_mfma_f32_32x32x16_bf16 v[98:113], v[150:153], v[170:173], v[98:113]
	ds_read_b128 v[200:203], v212 offset:36864
	ds_read_b128 v[180:183], v208 offset:36864
	s_waitcnt lgkmcnt(6)
	v_mfma_f32_32x32x16_bf16 v[82:97], v[154:157], v[166:169], v[82:97]
	ds_read_b128 v[184:187], v208 offset:40960
	ds_read_b128 v[188:191], v208 offset:45056
	v_mfma_f32_32x32x16_bf16 v[66:81], v[154:157], v[170:173], v[66:81]
	s_waitcnt lgkmcnt(7)
	v_mfma_f32_32x32x16_bf16 v[50:65], v[158:161], v[166:169], v[50:65]
	v_mfma_f32_32x32x16_bf16 v[34:49], v[158:161], v[170:173], v[34:49]
	s_waitcnt lgkmcnt(6)
	v_mfma_f32_32x32x16_bf16 v[18:33], v[162:165], v[166:169], v[18:33]
	v_mfma_f32_32x32x16_bf16 v[2:17], v[162:165], v[170:173], v[2:17]
	s_waitcnt vmcnt(0) lgkmcnt(0)
	s_barrier
	v_mfma_f32_32x32x16_bf16 v[114:129], v[174:177], v[192:195], v[114:129]
	ds_read_b128 v[150:153], v205 offset:0
	s_add_u32 m0, s14, 0x8020
	s_add_u32 s12, s1, s4
	s_addc_u32 s13, s3, s5
	global_load_lds_dwordx4 v149, s[12:13]
	v_mfma_f32_32x32x16_bf16 v[98:113], v[174:177], v[200:203], v[98:113]
	ds_read_b128 v[166:169], v209 offset:0
	s_add_u32 m0, s14, 0xa020
	s_add_u32 s12, s12, 0x20000
	s_addc_u32 s13, s13, 0
	global_load_lds_dwordx4 v149, s[12:13]
	v_mfma_f32_32x32x16_bf16 v[82:97], v[180:183], v[192:195], v[82:97]
	ds_read_b128 v[170:173], v209 offset:4096
	s_add_u32 m0, s14, 0xc020
	s_add_u32 s12, s12, 0x20000
	s_addc_u32 s13, s13, 0
	global_load_lds_dwordx4 v149, s[12:13]
	v_mfma_f32_32x32x16_bf16 v[66:81], v[180:183], v[200:203], v[66:81]
	ds_read_b128 v[154:157], v205 offset:4096
	s_add_u32 m0, s14, 0xe020
	s_add_u32 s12, s12, 0x20000
	s_addc_u32 s13, s13, 0
	global_load_lds_dwordx4 v149, s[12:13]
	v_mfma_f32_32x32x16_bf16 v[50:65], v[184:187], v[192:195], v[50:65]
	ds_read_b128 v[158:161], v205 offset:8192
	s_add_u32 m0, s14, 0x18020
	s_add_u32 s12, s10, s4
	s_addc_u32 s13, s11, s5
	global_load_lds_dwordx4 v149, s[12:13]
	v_mfma_f32_32x32x16_bf16 v[34:49], v[184:187], v[200:203], v[34:49]
	ds_read_b128 v[162:165], v205 offset:12288
	v_mfma_f32_32x32x16_bf16 v[18:33], v[188:191], v[192:195], v[18:33]
	v_mfma_f32_32x32x16_bf16 v[2:17], v[188:191], v[200:203], v[2:17]
	s_sub_u32 s9, s9, 1
	s_cmp_lg_u32 s9, 0
	s_cbranch_scc1 .Lg910_loop
	s_waitcnt lgkmcnt(4)
	v_mfma_f32_32x32x16_bf16 v[114:129], v[150:153], v[166:169], v[114:129]
	ds_read_b128 v[174:177], v206 offset:0
	s_waitcnt lgkmcnt(4)
	v_mfma_f32_32x32x16_bf16 v[98:113], v[150:153], v[170:173], v[98:113]
	ds_read_b128 v[192:195], v210 offset:0
	s_add_u32 m0, s14, 0x1a020
	s_add_u32 s12, s12, 0x20000
	s_addc_u32 s13, s13, 0
	global_load_lds_dwordx4 v149, s[12:13]
	s_waitcnt lgkmcnt(4)
	v_mfma_f32_32x32x16_bf16 v[82:97], v[154:157], v[166:169], v[82:97]
	ds_read_b128 v[200:203], v210 offset:4096
	v_mfma_f32_32x32x16_bf16 v[66:81], v[154:157], v[170:173], v[66:81]
	ds_read_b128 v[180:183], v206 offset:4096
	s_add_u32 m0, s14, 0x1c020
	s_add_u32 s12, s12, 0x20000
	s_addc_u32 s13, s13, 0
	global_load_lds_dwordx4 v149, s[12:13]
	s_waitcnt lgkmcnt(5)
	v_mfma_f32_32x32x16_bf16 v[50:65], v[158:161], v[166:169], v[50:65]
	ds_read_b128 v[184:187], v206 offset:8192
	v_mfma_f32_32x32x16_bf16 v[34:49], v[158:161], v[170:173], v[34:49]
	ds_read_b128 v[188:191], v206 offset:12288
	s_add_u32 m0, s14, 0x1e020
	s_add_u32 s12, s12, 0x20000
	s_addc_u32 s13, s13, 0
	global_load_lds_dwordx4 v149, s[12:13]
	s_add_u32 s4, s4, 0x80
	s_addc_u32 s5, s5, 0
	s_waitcnt lgkmcnt(6)
	v_mfma_f32_32x32x16_bf16 v[18:33], v[162:165], v[166:169], v[18:33]
	v_mfma_f32_32x32x16_bf16 v[2:17], v[162:165], v[170:173], v[2:17]
	s_waitcnt lgkmcnt(4)
	v_mfma_f32_32x32x16_bf16 v[114:129], v[174:177], v[192:195], v[114:129]
	ds_read_b128 v[150:153], v207 offset:0
	s_waitcnt lgkmcnt(4)
	v_mfma_f32_32x32x16_bf16 v[98:113], v[174:177], v[200:203], v[98:113]
	ds_read_b128 v[166:169], v211 offset:0
	s_waitcnt lgkmcnt(4)
	v_mfma_f32_32x32x16_bf16 v[82:97], v[180:183], v[192:195], v[82:97]
	ds_read_b128 v[170:173], v211 offset:4096
	v_mfma_f32_32x32x16_bf16 v[66:81], v[180:183], v[200:203], v[66:81]
	ds_read_b128 v[154:157], v207 offset:4096
	s_waitcnt lgkmcnt(5)
	v_mfma_f32_32x32x16_bf16 v[50:65], v[184:187], v[192:195], v[50:65]
	ds_read_b128 v[158:161], v207 offset:8192
	v_mfma_f32_32x32x16_bf16 v[34:49], v[184:187], v[200:203], v[34:49]
	ds_read_b128 v[162:165], v207 offset:12288
	s_waitcnt lgkmcnt(6)
	v_mfma_f32_32x32x16_bf16 v[18:33], v[188:191], v[192:195], v[18:33]
	v_mfma_f32_32x32x16_bf16 v[2:17], v[188:191], v[200:203], v[2:17]
	s_waitcnt lgkmcnt(4)
	v_mfma_f32_32x32x16_bf16 v[114:129], v[150:153], v[166:169], v[114:129]
	ds_read_b128 v[174:177], v208 offset:0
	ds_read_b128 v[192:195], v212 offset:0
	s_waitcnt lgkmcnt(5)
	v_mfma_f32_32x32x16_bf16 v[98:113], v[150:153], v[170:173], v[98:113]
	ds_read_b128 v[200:203], v212 offset:4096
	ds_read_b128 v[180:183], v208 offset:4096
	s_waitcnt lgkmcnt(6)
	v_mfma_f32_32x32x16_bf16 v[82:97], v[154:157], v[166:169], v[82:97]
	ds_read_b128 v[184:187], v208 offset:8192
	ds_read_b128 v[188:191], v208 offset:12288
	v_mfma_f32_32x32x16_bf16 v[66:81], v[154:157], v[170:173], v[66:81]
	s_waitcnt lgkmcnt(7)
	v_mfma_f32_32x32x16_bf16 v[50:65], v[158:161], v[166:169], v[50:65]
	v_mfma_f32_32x32x16_bf16 v[34:49], v[158:161], v[170:173], v[34:49]
	s_waitcnt lgkmcnt(6)
	v_mfma_f32_32x32x16_bf16 v[18:33], v[162:165], v[166:169], v[18:33]
	v_mfma_f32_32x32x16_bf16 v[2:17], v[162:165], v[170:173], v[2:17]
	s_waitcnt vmcnt(0) lgkmcnt(0)
	s_barrier
	v_mfma_f32_32x32x16_bf16 v[114:129], v[174:177], v[192:195], v[114:129]
	ds_read_b128 v[150:153], v205 offset:32768
	v_mfma_f32_32x32x16_bf16 v[98:113], v[174:177], v[200:203], v[98:113]
	ds_read_b128 v[166:169], v209 offset:32768
	v_mfma_f32_32x32x16_bf16 v[82:97], v[180:183], v[192:195], v[82:97]
	ds_read_b128 v[170:173], v209 offset:36864
	v_mfma_f32_32x32x16_bf16 v[66:81], v[180:183], v[200:203], v[66:81]
	ds_read_b128 v[154:157], v205 offset:36864
	v_mfma_f32_32x32x16_bf16 v[50:65], v[184:187], v[192:195], v[50:65]
	ds_read_b128 v[158:161], v205 offset:40960
	v_mfma_f32_32x32x16_bf16 v[34:49], v[184:187], v[200:203], v[34:49]
	ds_read_b128 v[162:165], v205 offset:45056
	v_mfma_f32_32x32x16_bf16 v[18:33], v[188:191], v[192:195], v[18:33]
	v_mfma_f32_32x32x16_bf16 v[2:17], v[188:191], v[200:203], v[2:17]
	s_waitcnt lgkmcnt(4)
	v_mfma_f32_32x32x16_bf16 v[114:129], v[150:153], v[166:169], v[114:129]
	ds_read_b128 v[174:177], v206 offset:32768
	s_waitcnt lgkmcnt(4)
	v_mfma_f32_32x32x16_bf16 v[98:113], v[150:153], v[170:173], v[98:113]
	ds_read_b128 v[192:195], v210 offset:32768
	s_waitcnt lgkmcnt(4)
	v_mfma_f32_32x32x16_bf16 v[82:97], v[154:157], v[166:169], v[82:97]
	ds_read_b128 v[200:203], v210 offset:36864
	v_mfma_f32_32x32x16_bf16 v[66:81], v[154:157], v[170:173], v[66:81]
	ds_read_b128 v[180:183], v206 offset:36864
	s_waitcnt lgkmcnt(5)
	v_mfma_f32_32x32x16_bf16 v[50:65], v[158:161], v[166:169], v[50:65]
	ds_read_b128 v[184:187], v206 offset:40960
	v_mfma_f32_32x32x16_bf16 v[34:49], v[158:161], v[170:173], v[34:49]
	ds_read_b128 v[188:191], v206 offset:45056
	s_waitcnt lgkmcnt(6)
	v_mfma_f32_32x32x16_bf16 v[18:33], v[162:165], v[166:169], v[18:33]
	v_mfma_f32_32x32x16_bf16 v[2:17], v[162:165], v[170:173], v[2:17]
	s_waitcnt lgkmcnt(4)
	v_mfma_f32_32x32x16_bf16 v[114:129], v[174:177], v[192:195], v[114:129]
	ds_read_b128 v[150:153], v207 offset:32768
	s_waitcnt lgkmcnt(4)
	v_mfma_f32_32x32x16_bf16 v[98:113], v[174:177], v[200:203], v[98:113]
	ds_read_b128 v[166:169], v211 offset:32768
	s_waitcnt lgkmcnt(4)
	v_mfma_f32_32x32x16_bf16 v[82:97], v[180:183], v[192:195], v[82:97]
	ds_read_b128 v[170:173], v211 offset:36864
	v_mfma_f32_32x32x16_bf16 v[66:81], v[180:183], v[200:203], v[66:81]
	ds_read_b128 v[154:157], v207 offset:36864
	s_waitcnt lgkmcnt(5)
	v_mfma_f32_32x32x16_bf16 v[50:65], v[184:187], v[192:195], v[50:65]
	ds_read_b128 v[158:161], v207 offset:40960
	v_mfma_f32_32x32x16_bf16 v[34:49], v[184:187], v[200:203], v[34:49]
	ds_read_b128 v[162:165], v207 offset:45056
	s_waitcnt lgkmcnt(6)
	v_mfma_f32_32x32x16_bf16 v[18:33], v[188:191], v[192:195], v[18:33]
	v_mfma_f32_32x32x16_bf16 v[2:17], v[188:191], v[200:203], v[2:17]
	s_waitcnt lgkmcnt(4)
	v_mfma_f32_32x32x16_bf16 v[114:129], v[150:153], v[166:169], v[114:129]
	ds_read_b128 v[174:177], v208 offset:32768
	ds_read_b128 v[192:195], v212 offset:32768
	s_waitcnt lgkmcnt(5)
	v_mfma_f32_32x32x16_bf16 v[98:113], v[150:153], v[170:173], v[98:113]
	ds_read_b128 v[200:203], v212 offset:36864
	ds_read_b128 v[180:183], v208 offset:36864
	s_waitcnt lgkmcnt(6)
	v_mfma_f32_32x32x16_bf16 v[82:97], v[154:157], v[166:169], v[82:97]
	ds_read_b128 v[184:187], v208 offset:40960
	ds_read_b128 v[188:191], v208 offset:45056
	v_mfma_f32_32x32x16_bf16 v[66:81], v[154:157], v[170:173], v[66:81]
	s_waitcnt lgkmcnt(7)
	v_mfma_f32_32x32x16_bf16 v[50:65], v[158:161], v[166:169], v[50:65]
	v_mfma_f32_32x32x16_bf16 v[34:49], v[158:161], v[170:173], v[34:49]
	s_waitcnt lgkmcnt(6)
	v_mfma_f32_32x32x16_bf16 v[18:33], v[162:165], v[166:169], v[18:33]
	v_mfma_f32_32x32x16_bf16 v[2:17], v[162:165], v[170:173], v[2:17]
	s_waitcnt vmcnt(0) lgkmcnt(0)
	s_barrier
	v_mfma_f32_32x32x16_bf16 v[114:129], v[174:177], v[192:195], v[114:129]
	v_mfma_f32_32x32x16_bf16 v[98:113], v[174:177], v[200:203], v[98:113]
	v_mfma_f32_32x32x16_bf16 v[82:97], v[180:183], v[192:195], v[82:97]
	v_mfma_f32_32x32x16_bf16 v[66:81], v[180:183], v[200:203], v[66:81]
	v_mfma_f32_32x32x16_bf16 v[50:65], v[184:187], v[192:195], v[50:65]
	v_mfma_f32_32x32x16_bf16 v[34:49], v[184:187], v[200:203], v[34:49]
	v_mfma_f32_32x32x16_bf16 v[18:33], v[188:191], v[192:195], v[18:33]
	v_mfma_f32_32x32x16_bf16 v[2:17], v[188:191], v[200:203], v[2:17]
	s_setprio 0
	v_add_u32_e32 v149, s0, v143
	v_or_b32_e32 v130, s2, v144
	s_mov_b32 s2, 0x7e07e07f
	v_mul_hi_i32 v0, v149, s2
	v_lshrrev_b32_e32 v131, 31, v0
	v_ashrrev_i32_e32 v0, 13, v0
	v_add_u32_e32 v0, v0, v131
	v_mul_i32_i24_e32 v131, 0x4100, v0
	v_sub_u32_e32 v131, v149, v131
	s_movk_i32 s3, 0xff
	v_mul_i32_i24_e32 v0, 0xc00, v0
	v_cmp_lt_i32_e32 vcc, s3, v131
	v_mov_b32_e32 v162, 0x1800
	v_mov_b32_e32 v152, v179
	s_waitcnt vmcnt(0)
	s_barrier
	v_cndmask_b32_e32 v150, v162, v0, vcc
	v_readlane_b32 s12, v251, 2
	v_and_b32_e32 v0, 31, v152
	v_bfe_u32 v131, v152, 5, 1
	v_mul_u32_u24_e32 v131, 0x240, v131
	v_lshlrev_b32_e32 v0, 2, v0
	v_add3_u32 v0, v145, v131, v0
	ds_write2_b32 v0, v114, v115 offset1:36
	ds_write2_b32 v0, v116, v117 offset0:72 offset1:108
	v_add_u32_e32 v114, 0x400, v0
	v_ashrrev_i32_e32 v151, 31, v150
	ds_write2_b32 v114, v118, v119 offset0:32 offset1:68
	ds_write2_b32 v114, v120, v121 offset0:104 offset1:140
	v_add_u32_e32 v114, 0x800, v0
	v_add_u32_e32 v0, 0xc00, v0
	v_readlane_b32 s26, v251, 16
	v_readlane_b32 s27, v251, 17
	ds_write2_b32 v114, v122, v123 offset0:64 offset1:100
	ds_write2_b32 v114, v124, v125 offset0:136 offset1:172
	ds_write2_b32 v0, v126, v127 offset0:96 offset1:132
	ds_write2_b32 v0, v128, v129 offset0:168 offset1:204
	v_lshl_add_u64 v[114:115], v[150:151], 2, s[26:27]
	s_mov_b64 s[4:5], 0x1b02000
	v_ashrrev_i32_e32 v131, 31, v130
	v_readlane_b32 s0, v251, 26
	v_lshlrev_b32_e32 v0, 3, v152
	v_lshl_add_u64 v[118:119], v[114:115], 0, s[4:5]
	v_lshlrev_b64 v[116:117], 2, v[130:131]
	v_readlane_b32 s1, v251, 27
	v_and_b32_e32 v122, 24, v0
	v_lshl_add_u64 v[120:121], v[118:119], 0, v[116:117]
	v_lshl_add_u64 v[114:115], v[130:131], 1, s[0:1]
	v_lshlrev_b32_e32 v0, 2, v122
	v_bfe_u32 v131, v152, 2, 4
	v_lshl_add_u64 v[158:159], v[120:121], 0, v[0:1]
	v_lshlrev_b32_e32 v120, 1, v122
	v_mul_u32_u24_e32 v122, 0x90, v131
	s_waitcnt lgkmcnt(0)
	v_add3_u32 v0, v145, v0, v122
	ds_read_b128 v[122:125], v0
	ds_read_b128 v[126:129], v0 offset:16
	global_load_dwordx4 v[150:153], v[158:159], off offset:16
	global_load_dwordx4 v[154:157], v[158:159], off
	v_or_b32_e32 v160, v131, v149
	v_mov_b32_e32 v121, v1
	v_ashrrev_i32_e32 v161, 31, v160
	v_lshl_add_u64 v[120:121], v[114:115], 0, v[120:121]
	v_readlane_b32 s13, v251, 3
	v_readlane_b32 s14, v251, 4
	v_readlane_b32 s15, v251, 5
	v_readlane_b32 s16, v251, 6
	v_readlane_b32 s17, v251, 7
	v_readlane_b32 s18, v251, 8
	v_readlane_b32 s19, v251, 9
	v_readlane_b32 s20, v251, 10
	v_readlane_b32 s21, v251, 11
	v_readlane_b32 s22, v251, 12
	v_readlane_b32 s23, v251, 13
	v_readlane_b32 s24, v251, 14
	v_readlane_b32 s25, v251, 15
	s_waitcnt vmcnt(1) lgkmcnt(0)
	v_pk_mul_f32 v[126:127], v[126:127], v[150:151]
	s_waitcnt vmcnt(0)
	v_pk_mul_f32 v[122:123], v[122:123], v[154:155]
	v_pk_mul_f32 v[124:125], v[124:125], v[156:157]
	v_pk_mul_f32 v[128:129], v[128:129], v[152:153]
	v_cvt_pk_bf16_f32 v122, v122, v123
	v_cvt_pk_bf16_f32 v123, v124, v125
	v_cvt_pk_bf16_f32 v124, v126, v127
	v_lshlrev_b64 v[126:127], 11, v[160:161]
	v_cvt_pk_bf16_f32 v125, v128, v129
	v_lshl_add_u64 v[126:127], v[120:121], 0, v[126:127]
	global_store_dwordx4 v[126:127], v[122:125], off
	ds_read_b128 v[122:125], v0 offset:2304
	ds_read_b128 v[126:129], v0 offset:2320
	s_waitcnt lgkmcnt(0)
	v_pk_mul_f32 v[126:127], v[126:127], v[150:151]
	v_pk_mul_f32 v[122:123], v[122:123], v[154:155]
	v_pk_mul_f32 v[124:125], v[124:125], v[156:157]
	v_cvt_pk_bf16_f32 v122, v122, v123
	v_cvt_pk_bf16_f32 v123, v124, v125
	v_cvt_pk_bf16_f32 v124, v126, v127
	v_or_b32_e32 v126, 16, v160
	v_ashrrev_i32_e32 v127, 31, v126
	v_pk_mul_f32 v[128:129], v[128:129], v[152:153]
	v_lshlrev_b64 v[126:127], 11, v[126:127]
	v_cvt_pk_bf16_f32 v125, v128, v129
	v_lshl_add_u64 v[120:121], v[120:121], 0, v[126:127]
	global_store_dwordx4 v[120:121], v[122:125], off
	v_mov_b32_e32 v120, v179
	v_or_b32_e32 v126, 32, v130
	v_and_b32_e32 v0, 31, v120
	v_bfe_u32 v121, v120, 5, 1
	v_mul_u32_u24_e32 v121, 0x240, v121
	v_lshlrev_b32_e32 v0, 2, v0
	v_add3_u32 v0, v145, v121, v0
	ds_write2_b32 v0, v98, v99 offset1:36
	ds_write2_b32 v0, v100, v101 offset0:72 offset1:108
	v_add_u32_e32 v98, 0x400, v0
	ds_write2_b32 v98, v102, v103 offset0:32 offset1:68
	ds_write2_b32 v98, v104, v105 offset0:104 offset1:140
	v_add_u32_e32 v98, 0x800, v0
	v_add_u32_e32 v0, 0xc00, v0
	ds_write2_b32 v98, v106, v107 offset0:64 offset1:100
	ds_write2_b32 v98, v108, v109 offset0:136 offset1:172
	ds_write2_b32 v0, v110, v111 offset0:96 offset1:132
	ds_write2_b32 v0, v112, v113 offset0:168 offset1:204
	v_lshlrev_b32_e32 v0, 3, v120
	v_and_b32_e32 v102, 24, v0
	v_ashrrev_i32_e32 v127, 31, v126
	v_lshlrev_b32_e32 v0, 2, v102
	v_lshl_add_u64 v[98:99], v[118:119], 0, v[0:1]
	v_lshlrev_b64 v[100:101], 2, v[126:127]
	v_lshl_add_u64 v[112:113], v[98:99], 0, v[100:101]
	v_lshlrev_b32_e32 v98, 1, v102
	v_mov_b32_e32 v99, v1
	v_bfe_u32 v128, v120, 2, 4
	v_lshl_add_u64 v[102:103], s[0:1], 0, v[98:99]
	v_mul_u32_u24_e32 v98, 0x90, v128
	s_waitcnt lgkmcnt(0)
	v_add3_u32 v0, v145, v0, v98
	ds_read_b128 v[104:107], v0
	ds_read_b128 v[108:111], v0 offset:16
	global_load_dwordx4 v[118:121], v[112:113], off offset:16
	global_load_dwordx4 v[122:125], v[112:113], off
	v_or_b32_e32 v128, v128, v149
	v_ashrrev_i32_e32 v129, 31, v128
	s_waitcnt vmcnt(1) lgkmcnt(0)
	v_pk_mul_f32 v[108:109], v[108:109], v[118:119]
	s_waitcnt vmcnt(0)
	v_pk_mul_f32 v[98:99], v[104:105], v[122:123]
	v_pk_mul_f32 v[106:107], v[106:107], v[124:125]
	v_cvt_pk_bf16_f32 v104, v98, v99
	v_lshlrev_b64 v[98:99], 11, v[128:129]
	v_pk_mul_f32 v[110:111], v[110:111], v[120:121]
	v_cvt_pk_bf16_f32 v105, v106, v107
	v_cvt_pk_bf16_f32 v106, v108, v109
	v_lshl_add_u64 v[108:109], v[102:103], 0, v[98:99]
	v_lshlrev_b64 v[98:99], 1, v[126:127]
	v_cvt_pk_bf16_f32 v107, v110, v111
	v_lshl_add_u64 v[108:109], v[108:109], 0, v[98:99]
	global_store_dwordx4 v[108:109], v[104:107], off
	ds_read_b128 v[104:107], v0 offset:2304
	ds_read_b128 v[108:111], v0 offset:2320
	s_waitcnt lgkmcnt(0)
	v_pk_mul_f32 v[108:109], v[108:109], v[118:119]
	v_pk_mul_f32 v[104:105], v[104:105], v[122:123]
	v_pk_mul_f32 v[106:107], v[106:107], v[124:125]
	v_cvt_pk_bf16_f32 v104, v104, v105
	v_cvt_pk_bf16_f32 v105, v106, v107
	v_cvt_pk_bf16_f32 v106, v108, v109
	v_or_b32_e32 v108, 16, v128
	v_ashrrev_i32_e32 v109, 31, v108
	v_lshlrev_b64 v[108:109], 11, v[108:109]
	v_pk_mul_f32 v[110:111], v[110:111], v[120:121]
	v_lshl_add_u64 v[102:103], v[102:103], 0, v[108:109]
	v_cvt_pk_bf16_f32 v107, v110, v111
	v_lshl_add_u64 v[102:103], v[102:103], 0, v[98:99]
	global_store_dwordx4 v[102:103], v[104:107], off
	v_or_b32_e32 v110, 32, v149
	v_mul_hi_i32 v0, v110, s2
	v_lshrrev_b32_e32 v102, 31, v0
	v_ashrrev_i32_e32 v0, 13, v0
	v_add_u32_e32 v0, v0, v102
	v_mul_i32_i24_e32 v102, 0x4100, v0
	v_sub_u32_e32 v102, v110, v102
	v_mul_i32_i24_e32 v0, 0xc00, v0
	v_cmp_lt_i32_e32 vcc, s3, v102
	v_mov_b32_e32 v104, v179
	s_nop 0
	v_cndmask_b32_e32 v102, v162, v0, vcc
	v_and_b32_e32 v0, 31, v104
	v_bfe_u32 v105, v104, 5, 1
	v_mul_u32_u24_e32 v105, 0x240, v105
	v_lshlrev_b32_e32 v0, 2, v0
	v_add3_u32 v0, v145, v105, v0
	ds_write2_b32 v0, v82, v83 offset1:36
	ds_write2_b32 v0, v84, v85 offset0:72 offset1:108
	v_add_u32_e32 v82, 0x400, v0
	v_ashrrev_i32_e32 v103, 31, v102
	ds_write2_b32 v82, v86, v87 offset0:32 offset1:68
	ds_write2_b32 v82, v88, v89 offset0:104 offset1:140
	v_add_u32_e32 v82, 0x800, v0
	v_add_u32_e32 v0, 0xc00, v0
	ds_write2_b32 v82, v90, v91 offset0:64 offset1:100
	ds_write2_b32 v82, v92, v93 offset0:136 offset1:172
	ds_write2_b32 v0, v94, v95 offset0:96 offset1:132
	ds_write2_b32 v0, v96, v97 offset0:168 offset1:204
	v_lshl_add_u64 v[82:83], v[102:103], 2, s[26:27]
	v_lshlrev_b32_e32 v0, 3, v104
	v_lshl_add_u64 v[82:83], v[82:83], 0, s[4:5]
	v_and_b32_e32 v86, 24, v0
	v_lshl_add_u64 v[84:85], v[82:83], 0, v[116:117]
	v_lshlrev_b32_e32 v0, 2, v86
	v_bfe_u32 v108, v104, 2, 4
	v_lshl_add_u64 v[106:107], v[84:85], 0, v[0:1]
	v_lshlrev_b32_e32 v84, 1, v86
	v_mul_u32_u24_e32 v86, 0x90, v108
	s_waitcnt lgkmcnt(0)
	v_add3_u32 v0, v145, v0, v86
	ds_read_b128 v[86:89], v0
	ds_read_b128 v[90:93], v0 offset:16
	global_load_dwordx4 v[94:97], v[106:107], off offset:16
	global_load_dwordx4 v[102:105], v[106:107], off
	v_or_b32_e32 v108, v108, v110
	v_mov_b32_e32 v85, v1
	v_ashrrev_i32_e32 v109, 31, v108
	v_lshl_add_u64 v[84:85], v[114:115], 0, v[84:85]
	s_waitcnt vmcnt(1) lgkmcnt(0)
	v_pk_mul_f32 v[90:91], v[90:91], v[94:95]
	s_waitcnt vmcnt(0)
	v_pk_mul_f32 v[86:87], v[86:87], v[102:103]
	v_pk_mul_f32 v[88:89], v[88:89], v[104:105]
	v_pk_mul_f32 v[92:93], v[92:93], v[96:97]
	v_cvt_pk_bf16_f32 v86, v86, v87
	v_cvt_pk_bf16_f32 v87, v88, v89
	v_cvt_pk_bf16_f32 v88, v90, v91
	v_lshlrev_b64 v[90:91], 11, v[108:109]
	v_cvt_pk_bf16_f32 v89, v92, v93
	v_lshl_add_u64 v[90:91], v[84:85], 0, v[90:91]
	global_store_dwordx4 v[90:91], v[86:89], off
	ds_read_b128 v[86:89], v0 offset:2304
	ds_read_b128 v[90:93], v0 offset:2320
	s_waitcnt lgkmcnt(0)
	v_pk_mul_f32 v[90:91], v[90:91], v[94:95]
	v_pk_mul_f32 v[86:87], v[86:87], v[102:103]
	v_pk_mul_f32 v[88:89], v[88:89], v[104:105]
	v_cvt_pk_bf16_f32 v86, v86, v87
	v_cvt_pk_bf16_f32 v87, v88, v89
	v_cvt_pk_bf16_f32 v88, v90, v91
	v_or_b32_e32 v90, 16, v108
	v_ashrrev_i32_e32 v91, 31, v90
	v_pk_mul_f32 v[92:93], v[92:93], v[96:97]
	v_lshlrev_b64 v[90:91], 11, v[90:91]
	v_cvt_pk_bf16_f32 v89, v92, v93
	v_lshl_add_u64 v[84:85], v[84:85], 0, v[90:91]
	global_store_dwordx4 v[84:85], v[86:89], off
	s_nop 1
	v_mov_b32_e32 v86, v179
	s_nop 0
	v_and_b32_e32 v0, 31, v86
	v_bfe_u32 v84, v86, 5, 1
	v_mul_u32_u24_e32 v84, 0x240, v84
	v_lshlrev_b32_e32 v0, 2, v0
	v_add3_u32 v0, v145, v84, v0
	ds_write2_b32 v0, v66, v67 offset1:36
	ds_write2_b32 v0, v68, v69 offset0:72 offset1:108
	v_add_u32_e32 v66, 0x400, v0
	ds_write2_b32 v66, v70, v71 offset0:32 offset1:68
	ds_write2_b32 v66, v72, v73 offset0:104 offset1:140
	v_add_u32_e32 v66, 0x800, v0
	v_add_u32_e32 v0, 0xc00, v0
	ds_write2_b32 v66, v74, v75 offset0:64 offset1:100
	ds_write2_b32 v66, v76, v77 offset0:136 offset1:172
	ds_write2_b32 v0, v78, v79 offset0:96 offset1:132
	ds_write2_b32 v0, v80, v81 offset0:168 offset1:204
	v_lshlrev_b32_e32 v0, 3, v86
	v_and_b32_e32 v68, 24, v0
	v_lshlrev_b32_e32 v0, 2, v68
	v_lshl_add_u64 v[66:67], v[82:83], 0, v[0:1]
	v_bfe_u32 v86, v86, 2, 4
	v_lshl_add_u64 v[84:85], v[66:67], 0, v[100:101]
	v_lshlrev_b32_e32 v66, 1, v68
	v_mul_u32_u24_e32 v68, 0x90, v86
	s_waitcnt lgkmcnt(0)
	v_add3_u32 v0, v145, v0, v68
	ds_read_b128 v[68:71], v0
	ds_read_b128 v[72:75], v0 offset:16
	global_load_dwordx4 v[76:79], v[84:85], off offset:16
	global_load_dwordx4 v[80:83], v[84:85], off
	v_or_b32_e32 v86, v86, v110
	v_mov_b32_e32 v67, v1
	v_ashrrev_i32_e32 v87, 31, v86
	v_lshl_add_u64 v[66:67], s[0:1], 0, v[66:67]
	s_waitcnt vmcnt(1) lgkmcnt(0)
	v_pk_mul_f32 v[72:73], v[72:73], v[76:77]
	s_waitcnt vmcnt(0)
	v_pk_mul_f32 v[68:69], v[68:69], v[80:81]
	v_pk_mul_f32 v[70:71], v[70:71], v[82:83]
	v_cvt_pk_bf16_f32 v68, v68, v69
	v_cvt_pk_bf16_f32 v69, v70, v71
	v_cvt_pk_bf16_f32 v70, v72, v73
	v_lshlrev_b64 v[72:73], 11, v[86:87]
	v_pk_mul_f32 v[74:75], v[74:75], v[78:79]
	v_lshl_add_u64 v[72:73], v[66:67], 0, v[72:73]
	v_cvt_pk_bf16_f32 v71, v74, v75
	v_lshl_add_u64 v[72:73], v[72:73], 0, v[98:99]
	global_store_dwordx4 v[72:73], v[68:71], off
	ds_read_b128 v[68:71], v0 offset:2304
	ds_read_b128 v[72:75], v0 offset:2320
	s_waitcnt lgkmcnt(0)
	v_pk_mul_f32 v[72:73], v[72:73], v[76:77]
	v_pk_mul_f32 v[68:69], v[68:69], v[80:81]
	v_pk_mul_f32 v[70:71], v[70:71], v[82:83]
	v_cvt_pk_bf16_f32 v68, v68, v69
	v_cvt_pk_bf16_f32 v69, v70, v71
	v_cvt_pk_bf16_f32 v70, v72, v73
	v_or_b32_e32 v72, 16, v86
	v_ashrrev_i32_e32 v73, 31, v72
	v_lshlrev_b64 v[72:73], 11, v[72:73]
	v_pk_mul_f32 v[74:75], v[74:75], v[78:79]
	v_lshl_add_u64 v[66:67], v[66:67], 0, v[72:73]
	v_cvt_pk_bf16_f32 v71, v74, v75
	v_lshl_add_u64 v[66:67], v[66:67], 0, v[98:99]
	global_store_dwordx4 v[66:67], v[68:71], off
	v_or_b32_e32 v74, 64, v149
	v_mul_hi_i32 v0, v74, s2
	v_lshrrev_b32_e32 v66, 31, v0
	v_ashrrev_i32_e32 v0, 13, v0
	v_add_u32_e32 v0, v0, v66
	v_mul_i32_i24_e32 v66, 0x4100, v0
	v_sub_u32_e32 v66, v74, v66
	v_mul_i32_i24_e32 v0, 0xc00, v0
	v_cmp_lt_i32_e32 vcc, s3, v66
	v_mov_b32_e32 v68, v179
	s_nop 0
	v_cndmask_b32_e32 v66, v162, v0, vcc
	v_and_b32_e32 v0, 31, v68
	v_bfe_u32 v69, v68, 5, 1
	v_mul_u32_u24_e32 v69, 0x240, v69
	v_lshlrev_b32_e32 v0, 2, v0
	v_add3_u32 v0, v145, v69, v0
	ds_write2_b32 v0, v50, v51 offset1:36
	ds_write2_b32 v0, v52, v53 offset0:72 offset1:108
	v_add_u32_e32 v50, 0x400, v0
	v_ashrrev_i32_e32 v67, 31, v66
	ds_write2_b32 v50, v54, v55 offset0:32 offset1:68
	ds_write2_b32 v50, v56, v57 offset0:104 offset1:140
	v_add_u32_e32 v50, 0x800, v0
	v_add_u32_e32 v0, 0xc00, v0
	ds_write2_b32 v50, v58, v59 offset0:64 offset1:100
	ds_write2_b32 v50, v60, v61 offset0:136 offset1:172
	ds_write2_b32 v0, v62, v63 offset0:96 offset1:132
	ds_write2_b32 v0, v64, v65 offset0:168 offset1:204
	v_lshl_add_u64 v[50:51], v[66:67], 2, s[26:27]
	v_lshlrev_b32_e32 v0, 3, v68
	v_lshl_add_u64 v[50:51], v[50:51], 0, s[4:5]
	v_and_b32_e32 v54, 24, v0
	v_lshl_add_u64 v[52:53], v[50:51], 0, v[116:117]
	v_lshlrev_b32_e32 v0, 2, v54
	v_bfe_u32 v72, v68, 2, 4
	v_lshl_add_u64 v[70:71], v[52:53], 0, v[0:1]
	v_lshlrev_b32_e32 v52, 1, v54
	v_mul_u32_u24_e32 v54, 0x90, v72
	s_waitcnt lgkmcnt(0)
	v_add3_u32 v0, v145, v0, v54
	ds_read_b128 v[54:57], v0
	ds_read_b128 v[58:61], v0 offset:16
	global_load_dwordx4 v[62:65], v[70:71], off offset:16
	global_load_dwordx4 v[66:69], v[70:71], off
	v_or_b32_e32 v72, v72, v74
	v_mov_b32_e32 v53, v1
	v_ashrrev_i32_e32 v73, 31, v72
	v_lshl_add_u64 v[52:53], v[114:115], 0, v[52:53]
	s_waitcnt vmcnt(1) lgkmcnt(0)
	v_pk_mul_f32 v[58:59], v[58:59], v[62:63]
	s_waitcnt vmcnt(0)
	v_pk_mul_f32 v[54:55], v[54:55], v[66:67]
	v_pk_mul_f32 v[56:57], v[56:57], v[68:69]
	v_pk_mul_f32 v[60:61], v[60:61], v[64:65]
	v_cvt_pk_bf16_f32 v54, v54, v55
	v_cvt_pk_bf16_f32 v55, v56, v57
	v_cvt_pk_bf16_f32 v56, v58, v59
	v_lshlrev_b64 v[58:59], 11, v[72:73]
	v_cvt_pk_bf16_f32 v57, v60, v61
	v_lshl_add_u64 v[58:59], v[52:53], 0, v[58:59]
	global_store_dwordx4 v[58:59], v[54:57], off
	ds_read_b128 v[54:57], v0 offset:2304
	ds_read_b128 v[58:61], v0 offset:2320
	s_waitcnt lgkmcnt(0)
	v_pk_mul_f32 v[58:59], v[58:59], v[62:63]
	v_pk_mul_f32 v[54:55], v[54:55], v[66:67]
	v_pk_mul_f32 v[56:57], v[56:57], v[68:69]
	v_cvt_pk_bf16_f32 v54, v54, v55
	v_cvt_pk_bf16_f32 v55, v56, v57
	v_cvt_pk_bf16_f32 v56, v58, v59
	v_or_b32_e32 v58, 16, v72
	v_ashrrev_i32_e32 v59, 31, v58
	v_pk_mul_f32 v[60:61], v[60:61], v[64:65]
	v_lshlrev_b64 v[58:59], 11, v[58:59]
	v_cvt_pk_bf16_f32 v57, v60, v61
	v_lshl_add_u64 v[52:53], v[52:53], 0, v[58:59]
	global_store_dwordx4 v[52:53], v[54:57], off
	s_nop 1
	v_mov_b32_e32 v54, v179
	s_nop 0
	v_and_b32_e32 v0, 31, v54
	v_bfe_u32 v52, v54, 5, 1
	v_mul_u32_u24_e32 v52, 0x240, v52
	v_lshlrev_b32_e32 v0, 2, v0
	v_add3_u32 v0, v145, v52, v0
	ds_write2_b32 v0, v34, v35 offset1:36
	ds_write2_b32 v0, v36, v37 offset0:72 offset1:108
	v_add_u32_e32 v34, 0x400, v0
	ds_write2_b32 v34, v38, v39 offset0:32 offset1:68
	ds_write2_b32 v34, v40, v41 offset0:104 offset1:140
	v_add_u32_e32 v34, 0x800, v0
	v_add_u32_e32 v0, 0xc00, v0
	ds_write2_b32 v34, v42, v43 offset0:64 offset1:100
	ds_write2_b32 v34, v44, v45 offset0:136 offset1:172
	ds_write2_b32 v0, v46, v47 offset0:96 offset1:132
	ds_write2_b32 v0, v48, v49 offset0:168 offset1:204
	v_lshlrev_b32_e32 v0, 3, v54
	v_and_b32_e32 v36, 24, v0
	v_lshlrev_b32_e32 v0, 2, v36
	v_lshl_add_u64 v[34:35], v[50:51], 0, v[0:1]
	v_bfe_u32 v54, v54, 2, 4
	v_lshl_add_u64 v[52:53], v[34:35], 0, v[100:101]
	v_lshlrev_b32_e32 v34, 1, v36
	v_mul_u32_u24_e32 v36, 0x90, v54
	s_waitcnt lgkmcnt(0)
	v_add3_u32 v0, v145, v0, v36
	ds_read_b128 v[36:39], v0
	ds_read_b128 v[40:43], v0 offset:16
	global_load_dwordx4 v[44:47], v[52:53], off offset:16
	global_load_dwordx4 v[48:51], v[52:53], off
	v_or_b32_e32 v54, v54, v74
	v_mov_b32_e32 v35, v1
	v_ashrrev_i32_e32 v55, 31, v54
	v_lshl_add_u64 v[34:35], s[0:1], 0, v[34:35]
	s_waitcnt vmcnt(1) lgkmcnt(0)
	v_pk_mul_f32 v[40:41], v[40:41], v[44:45]
	s_waitcnt vmcnt(0)
	v_pk_mul_f32 v[36:37], v[36:37], v[48:49]
	v_pk_mul_f32 v[38:39], v[38:39], v[50:51]
	v_cvt_pk_bf16_f32 v36, v36, v37
	v_cvt_pk_bf16_f32 v37, v38, v39
	v_cvt_pk_bf16_f32 v38, v40, v41
	v_lshlrev_b64 v[40:41], 11, v[54:55]
	v_pk_mul_f32 v[42:43], v[42:43], v[46:47]
	v_lshl_add_u64 v[40:41], v[34:35], 0, v[40:41]
	v_cvt_pk_bf16_f32 v39, v42, v43
	v_lshl_add_u64 v[40:41], v[40:41], 0, v[98:99]
	global_store_dwordx4 v[40:41], v[36:39], off
	ds_read_b128 v[36:39], v0 offset:2304
	ds_read_b128 v[40:43], v0 offset:2320
	s_waitcnt lgkmcnt(0)
	v_pk_mul_f32 v[40:41], v[40:41], v[44:45]
	v_pk_mul_f32 v[36:37], v[36:37], v[48:49]
	v_pk_mul_f32 v[38:39], v[38:39], v[50:51]
	v_cvt_pk_bf16_f32 v36, v36, v37
	v_cvt_pk_bf16_f32 v37, v38, v39
	v_cvt_pk_bf16_f32 v38, v40, v41
	v_or_b32_e32 v40, 16, v54
	v_ashrrev_i32_e32 v41, 31, v40
	v_lshlrev_b64 v[40:41], 11, v[40:41]
	v_pk_mul_f32 v[42:43], v[42:43], v[46:47]
	v_lshl_add_u64 v[34:35], v[34:35], 0, v[40:41]
	v_cvt_pk_bf16_f32 v39, v42, v43
	v_lshl_add_u64 v[34:35], v[34:35], 0, v[98:99]
	global_store_dwordx4 v[34:35], v[36:39], off
	v_or_b32_e32 v42, 0x60, v149
	v_mul_hi_i32 v0, v42, s2
	v_lshrrev_b32_e32 v34, 31, v0
	v_ashrrev_i32_e32 v0, 13, v0
	v_add_u32_e32 v0, v0, v34
	v_mul_i32_i24_e32 v34, 0x4100, v0
	v_sub_u32_e32 v34, v42, v34
	v_mul_i32_i24_e32 v0, 0xc00, v0
	v_cmp_lt_i32_e32 vcc, s3, v34
	v_mov_b32_e32 v36, v179
	s_nop 0
	v_cndmask_b32_e32 v34, v162, v0, vcc
	v_and_b32_e32 v0, 31, v36
	v_bfe_u32 v37, v36, 5, 1
	v_mul_u32_u24_e32 v37, 0x240, v37
	v_lshlrev_b32_e32 v0, 2, v0
	v_add3_u32 v0, v145, v37, v0
	ds_write2_b32 v0, v18, v19 offset1:36
	ds_write2_b32 v0, v20, v21 offset0:72 offset1:108
	v_add_u32_e32 v18, 0x400, v0
	v_ashrrev_i32_e32 v35, 31, v34
	ds_write2_b32 v18, v22, v23 offset0:32 offset1:68
	ds_write2_b32 v18, v24, v25 offset0:104 offset1:140
	v_add_u32_e32 v18, 0x800, v0
	v_add_u32_e32 v0, 0xc00, v0
	ds_write2_b32 v18, v26, v27 offset0:64 offset1:100
	ds_write2_b32 v18, v28, v29 offset0:136 offset1:172
	ds_write2_b32 v0, v30, v31 offset0:96 offset1:132
	ds_write2_b32 v0, v32, v33 offset0:168 offset1:204
	v_lshl_add_u64 v[18:19], v[34:35], 2, s[26:27]
	v_lshlrev_b32_e32 v0, 3, v36
	v_lshl_add_u64 v[18:19], v[18:19], 0, s[4:5]
	v_and_b32_e32 v22, 24, v0
	v_lshl_add_u64 v[20:21], v[18:19], 0, v[116:117]
	v_lshlrev_b32_e32 v0, 2, v22
	v_bfe_u32 v40, v36, 2, 4
	v_lshl_add_u64 v[38:39], v[20:21], 0, v[0:1]
	v_lshlrev_b32_e32 v20, 1, v22
	v_mul_u32_u24_e32 v22, 0x90, v40
	s_waitcnt lgkmcnt(0)
	v_add3_u32 v0, v145, v0, v22
	ds_read_b128 v[22:25], v0
	ds_read_b128 v[26:29], v0 offset:16
	global_load_dwordx4 v[30:33], v[38:39], off offset:16
	global_load_dwordx4 v[34:37], v[38:39], off
	v_or_b32_e32 v40, v40, v42
	v_mov_b32_e32 v21, v1
	v_ashrrev_i32_e32 v41, 31, v40
	v_lshl_add_u64 v[20:21], v[114:115], 0, v[20:21]
	s_waitcnt vmcnt(1) lgkmcnt(0)
	v_pk_mul_f32 v[26:27], v[26:27], v[30:31]
	s_waitcnt vmcnt(0)
	v_pk_mul_f32 v[22:23], v[22:23], v[34:35]
	v_pk_mul_f32 v[24:25], v[24:25], v[36:37]
	v_pk_mul_f32 v[28:29], v[28:29], v[32:33]
	v_cvt_pk_bf16_f32 v22, v22, v23
	v_cvt_pk_bf16_f32 v23, v24, v25
	v_cvt_pk_bf16_f32 v24, v26, v27
	v_lshlrev_b64 v[26:27], 11, v[40:41]
	v_cvt_pk_bf16_f32 v25, v28, v29
	v_lshl_add_u64 v[26:27], v[20:21], 0, v[26:27]
	global_store_dwordx4 v[26:27], v[22:25], off
	ds_read_b128 v[22:25], v0 offset:2304
	ds_read_b128 v[26:29], v0 offset:2320
	s_waitcnt lgkmcnt(0)
	v_pk_mul_f32 v[26:27], v[26:27], v[30:31]
	v_pk_mul_f32 v[22:23], v[22:23], v[34:35]
	v_pk_mul_f32 v[24:25], v[24:25], v[36:37]
	v_cvt_pk_bf16_f32 v22, v22, v23
	v_cvt_pk_bf16_f32 v23, v24, v25
	v_cvt_pk_bf16_f32 v24, v26, v27
	v_or_b32_e32 v26, 16, v40
	v_ashrrev_i32_e32 v27, 31, v26
	v_pk_mul_f32 v[28:29], v[28:29], v[32:33]
	v_lshlrev_b64 v[26:27], 11, v[26:27]
	v_cvt_pk_bf16_f32 v25, v28, v29
	v_lshl_add_u64 v[20:21], v[20:21], 0, v[26:27]
	global_store_dwordx4 v[20:21], v[22:25], off
	s_nop 1
	v_mov_b32_e32 v22, v179
	s_nop 0
	v_and_b32_e32 v0, 31, v22
	v_bfe_u32 v20, v22, 5, 1
	v_mul_u32_u24_e32 v20, 0x240, v20
	v_lshlrev_b32_e32 v0, 2, v0
	v_add3_u32 v0, v145, v20, v0
	ds_write2_b32 v0, v2, v3 offset1:36
	ds_write2_b32 v0, v4, v5 offset0:72 offset1:108
	v_add_u32_e32 v2, 0x400, v0
	ds_write2_b32 v2, v6, v7 offset0:32 offset1:68
	ds_write2_b32 v2, v8, v9 offset0:104 offset1:140
	v_add_u32_e32 v2, 0x800, v0
	v_add_u32_e32 v0, 0xc00, v0
	ds_write2_b32 v2, v10, v11 offset0:64 offset1:100
	ds_write2_b32 v2, v12, v13 offset0:136 offset1:172
	ds_write2_b32 v0, v14, v15 offset0:96 offset1:132
	ds_write2_b32 v0, v16, v17 offset0:168 offset1:204
	v_lshlrev_b32_e32 v0, 3, v22
	v_and_b32_e32 v4, 24, v0
	v_lshlrev_b32_e32 v0, 2, v4
	v_lshl_add_u64 v[2:3], v[18:19], 0, v[0:1]
	v_bfe_u32 v22, v22, 2, 4
	v_lshl_add_u64 v[20:21], v[2:3], 0, v[100:101]
	v_lshlrev_b32_e32 v2, 1, v4
	v_mul_u32_u24_e32 v4, 0x90, v22
	s_waitcnt lgkmcnt(0)
	v_add3_u32 v0, v145, v0, v4
	ds_read_b128 v[4:7], v0
	ds_read_b128 v[8:11], v0 offset:16
	global_load_dwordx4 v[12:15], v[20:21], off offset:16
	global_load_dwordx4 v[16:19], v[20:21], off
	v_or_b32_e32 v22, v22, v42
	v_mov_b32_e32 v3, v1
	v_ashrrev_i32_e32 v23, 31, v22
	v_lshl_add_u64 v[2:3], s[0:1], 0, v[2:3]
	s_waitcnt vmcnt(1) lgkmcnt(0)
	v_pk_mul_f32 v[8:9], v[8:9], v[12:13]
	s_waitcnt vmcnt(0)
	v_pk_mul_f32 v[4:5], v[4:5], v[16:17]
	v_pk_mul_f32 v[6:7], v[6:7], v[18:19]
	v_cvt_pk_bf16_f32 v4, v4, v5
	v_cvt_pk_bf16_f32 v5, v6, v7
	v_cvt_pk_bf16_f32 v6, v8, v9
	v_lshlrev_b64 v[8:9], 11, v[22:23]
	v_pk_mul_f32 v[10:11], v[10:11], v[14:15]
	v_lshl_add_u64 v[8:9], v[2:3], 0, v[8:9]
	v_cvt_pk_bf16_f32 v7, v10, v11
	v_lshl_add_u64 v[8:9], v[8:9], 0, v[98:99]
	global_store_dwordx4 v[8:9], v[4:7], off
	ds_read_b128 v[4:7], v0 offset:2304
	ds_read_b128 v[8:11], v0 offset:2320
	s_waitcnt lgkmcnt(0)
	v_pk_mul_f32 v[8:9], v[8:9], v[12:13]
	v_pk_mul_f32 v[4:5], v[4:5], v[16:17]
	v_pk_mul_f32 v[6:7], v[6:7], v[18:19]
	v_cvt_pk_bf16_f32 v4, v4, v5
	v_cvt_pk_bf16_f32 v5, v6, v7
	v_cvt_pk_bf16_f32 v6, v8, v9
	v_or_b32_e32 v8, 16, v22
	v_ashrrev_i32_e32 v9, 31, v8
	v_lshlrev_b64 v[8:9], 11, v[8:9]
	v_pk_mul_f32 v[10:11], v[10:11], v[14:15]
	v_lshl_add_u64 v[2:3], v[2:3], 0, v[8:9]
	v_cvt_pk_bf16_f32 v7, v10, v11
	v_lshl_add_u64 v[2:3], v[2:3], 0, v[98:99]
	global_store_dwordx4 v[2:3], v[4:7], off
	s_add_i32 s7, s7, s6
	s_cmpk_gt_i32 s7, 0x207
	s_cselect_b64 s[0:1], -1, 0
	s_branch .LBB0_907
